# HGRN scan staging waves: next-iteration prefetch loads issued before the half-chunk barrier
# baseline (speedup 1.0000x reference)
.Lscanh_loop:
	s_waitcnt vmcnt(9)
	v_lshlrev_b32_e32 v80, 16, v12
	v_and_b32_e32 v81, 0xffff0000, v12
	v_lshlrev_b32_e32 v82, 16, v16
	v_and_b32_e32 v83, 0xffff0000, v16
	v_lshlrev_b32_e32 v84, 16, v13
	v_and_b32_e32 v85, 0xffff0000, v13
	v_lshlrev_b32_e32 v86, 16, v17
	v_and_b32_e32 v87, 0xffff0000, v17
	v_mul_f32_e32 v80, v80, v82
	v_mul_f32_e32 v81, v81, v83
	v_mul_f32_e32 v84, v84, v86
	v_mul_f32_e32 v85, v85, v87
	v_cvt_pk_bf16_f32 v76, v80, v81
	v_cvt_pk_bf16_f32 v77, v84, v85
	v_lshlrev_b32_e32 v80, 16, v14
	v_and_b32_e32 v81, 0xffff0000, v14
	v_lshlrev_b32_e32 v82, 16, v18
	v_and_b32_e32 v83, 0xffff0000, v18
	v_lshlrev_b32_e32 v84, 16, v15
	v_and_b32_e32 v85, 0xffff0000, v15
	v_lshlrev_b32_e32 v86, 16, v19
	v_and_b32_e32 v87, 0xffff0000, v19
	v_mul_f32_e32 v80, v80, v82
	v_mul_f32_e32 v81, v81, v83
	v_mul_f32_e32 v84, v84, v86
	v_mul_f32_e32 v85, v85, v87
	v_cvt_pk_bf16_f32 v78, v80, v81
	v_cvt_pk_bf16_f32 v79, v84, v85
	v_lshlrev_b32_e32 v80, 16, v196
	v_and_b32_e32 v81, 0xffff0000, v196
	v_lshlrev_b32_e32 v82, 16, v200
	v_and_b32_e32 v83, 0xffff0000, v200
	v_lshlrev_b32_e32 v84, 16, v197
	v_and_b32_e32 v85, 0xffff0000, v197
	v_lshlrev_b32_e32 v86, 16, v201
	v_and_b32_e32 v87, 0xffff0000, v201
	v_mul_f32_e32 v80, v80, v82
	v_mul_f32_e32 v81, v81, v83
	v_mul_f32_e32 v84, v84, v86
	v_mul_f32_e32 v85, v85, v87
	v_cvt_pk_bf16_f32 v246, v80, v81
	v_cvt_pk_bf16_f32 v247, v84, v85
	v_lshlrev_b32_e32 v80, 16, v198
	v_and_b32_e32 v81, 0xffff0000, v198
	v_lshlrev_b32_e32 v82, 16, v202
	v_and_b32_e32 v83, 0xffff0000, v202
	v_lshlrev_b32_e32 v84, 16, v199
	v_and_b32_e32 v85, 0xffff0000, v199
	v_lshlrev_b32_e32 v86, 16, v203
	v_and_b32_e32 v87, 0xffff0000, v203
	v_mul_f32_e32 v80, v80, v82
	v_mul_f32_e32 v81, v81, v83
	v_mul_f32_e32 v84, v84, v86
	v_mul_f32_e32 v85, v85, v87
	v_cvt_pk_bf16_f32 v248, v80, v81
	v_cvt_pk_bf16_f32 v249, v84, v85
	ds_write_b128 v158, v[76:79]
	ds_write_b128 v158, v[20:23] offset:8704
	ds_write_b128 v158, v[24:27] offset:17408
	ds_write_b128 v228, v[246:249]
	ds_write_b128 v228, v[204:207] offset:8704
	ds_write_b128 v228, v[208:211] offset:17408
	s_and_saveexec_b64 s[14:15], s[2:3]
	ds_write_b128 v229, v[4:7] offset:26112
	s_or_b64 exec, exec, s[14:15]
	s_add_i32 s75, s76, 2
	s_cmpk_lt_u32 s76, 0x46
	s_cselect_b64 s[56:57], -1, 0
	s_cmpk_gt_u32 s76, 0x45
	s_cselect_b64 s[54:55], -1, 0
	s_waitcnt lgkmcnt(0)
	s_and_b64 vcc, exec, s[54:55]
	s_cbranch_vccnz .Lscanh_nopfax
	s_and_b64 vcc, exec, s[12:13]
	v_lshl_add_u32 v0, s75, 5, v113
	s_cbranch_vccnz .Lscanh_ia
	v_add3_u32 v1, v113, s74, 64
	v_cmp_lt_i32_e32 vcc, s47, v1
	s_and_saveexec_b64 s[14:15], vcc
	s_xor_b64 s[14:15], exec, s[14:15]
	v_add_u32_e32 v0, s38, v156
	v_add_u32_e32 v0, 0x9df, v0
	s_andn2_saveexec_b64 s[14:15], s[14:15]
	v_sub_u32_e32 v0, 0xff, v0
	s_or_b64 exec, exec, s[14:15]

.Lscanh_nopfax:
	s_barrier
	s_cmp_eq_u32 s76, 0
	s_cbranch_scc1 .Lscanh_nordb
	ds_read_b128 v[88:91], v96 offset:4608
.Lscanh_nordb:
.Lscanh_nopfa:
	s_cmp_eq_u32 s76, 0
	s_cbranch_scc1 .Lscanh_nocpb
	s_mov_b32 s14, s77
	s_add_u32 s14, s50, s14
	s_addc_u32 s15, s51, 0
	s_lshl_b64 s[14:15], s[14:15], 11
	s_add_u32 s14, s14, s78
	s_addc_u32 s15, s15, s79
	s_waitcnt lgkmcnt(0)
	v_lshl_add_u64 v[92:93], v[94:95], 0, s[14:15]
	global_store_dwordx4 v[92:93], v[88:91], off

.Lscanh_steady:
	s_waitcnt vmcnt(9)
	v_lshlrev_b32_e32 v80, 16, v28
	v_and_b32_e32 v81, 0xffff0000, v28
	v_lshlrev_b32_e32 v82, 16, v32
	v_and_b32_e32 v83, 0xffff0000, v32
	v_lshlrev_b32_e32 v84, 16, v29
	v_and_b32_e32 v85, 0xffff0000, v29
	v_lshlrev_b32_e32 v86, 16, v33
	v_and_b32_e32 v87, 0xffff0000, v33
	v_mul_f32_e32 v80, v80, v82
	v_mul_f32_e32 v81, v81, v83
	v_mul_f32_e32 v84, v84, v86
	v_mul_f32_e32 v85, v85, v87
	v_cvt_pk_bf16_f32 v68, v80, v81
	v_cvt_pk_bf16_f32 v69, v84, v85
	v_lshlrev_b32_e32 v80, 16, v30
	v_and_b32_e32 v81, 0xffff0000, v30
	v_lshlrev_b32_e32 v82, 16, v34
	v_and_b32_e32 v83, 0xffff0000, v34
	v_lshlrev_b32_e32 v84, 16, v31
	v_and_b32_e32 v85, 0xffff0000, v31
	v_lshlrev_b32_e32 v86, 16, v35
	v_and_b32_e32 v87, 0xffff0000, v35
	v_mul_f32_e32 v80, v80, v82
	v_mul_f32_e32 v81, v81, v83
	v_mul_f32_e32 v84, v84, v86
	v_mul_f32_e32 v85, v85, v87
	v_cvt_pk_bf16_f32 v70, v80, v81
	v_cvt_pk_bf16_f32 v71, v84, v85
	v_lshlrev_b32_e32 v80, 16, v212
	v_and_b32_e32 v81, 0xffff0000, v212
	v_lshlrev_b32_e32 v82, 16, v216
	v_and_b32_e32 v83, 0xffff0000, v216
	v_lshlrev_b32_e32 v84, 16, v213
	v_and_b32_e32 v85, 0xffff0000, v213
	v_lshlrev_b32_e32 v86, 16, v217
	v_and_b32_e32 v87, 0xffff0000, v217
	v_mul_f32_e32 v80, v80, v82
	v_mul_f32_e32 v81, v81, v83
	v_mul_f32_e32 v84, v84, v86
	v_mul_f32_e32 v85, v85, v87
	v_cvt_pk_bf16_f32 v246, v80, v81
	v_cvt_pk_bf16_f32 v247, v84, v85
	v_lshlrev_b32_e32 v80, 16, v214
	v_and_b32_e32 v81, 0xffff0000, v214
	v_lshlrev_b32_e32 v82, 16, v218
	v_and_b32_e32 v83, 0xffff0000, v218
	v_lshlrev_b32_e32 v84, 16, v215
	v_and_b32_e32 v85, 0xffff0000, v215
	v_lshlrev_b32_e32 v86, 16, v219
	v_and_b32_e32 v87, 0xffff0000, v219
	v_mul_f32_e32 v80, v80, v82
	v_mul_f32_e32 v81, v81, v83
	v_mul_f32_e32 v84, v84, v86
	v_mul_f32_e32 v85, v85, v87
	v_cvt_pk_bf16_f32 v248, v80, v81
	v_cvt_pk_bf16_f32 v249, v84, v85
	ds_write_b128 v158, v[68:71] offset:32768
	ds_write_b128 v158, v[36:39] offset:41472
	ds_write_b128 v158, v[40:43] offset:50176
	ds_write_b128 v228, v[246:249] offset:32768
	ds_write_b128 v228, v[220:223] offset:41472
	ds_write_b128 v228, v[224:227] offset:50176
	s_and_saveexec_b64 s[14:15], s[2:3]
	ds_write_b128 v229, v[8:11] offset:58880
	s_or_b64 exec, exec, s[14:15]
	s_waitcnt lgkmcnt(0)
	s_andn2_b64 vcc, exec, s[56:57]
	s_cbranch_vccnz .Lscanh_nopfbx
	s_lshl_b32 s14, s76, 5
	s_addk_i32 s14, 0x60
	s_and_b64 vcc, exec, s[12:13]
	v_add_u32_e32 v0, s14, v113
	s_cbranch_vccnz .Lscanh_ib
	v_add_u32_e32 v1, s74, v113
	v_add_u32_e32 v1, 0x60, v1
	v_cmp_lt_i32_e32 vcc, s47, v1
	s_and_saveexec_b64 s[14:15], vcc
	s_xor_b64 s[14:15], exec, s[14:15]
	v_add_u32_e32 v0, s38, v156
	v_add_u32_e32 v0, 0x9bf, v0
	s_andn2_saveexec_b64 s[14:15], s[14:15]
	v_sub_u32_e32 v0, 0xff, v0
	s_or_b64 exec, exec, s[14:15]

.Lscanh_nopfbx:
	s_barrier
	ds_read_b128 v[88:91], v96 offset:0
